# attention weights via prefix products of (1+e) with one rcp per 8 keys, both bpermutes issued together, masks via 2-op compare/select
# speedup vs baseline: 1.0288x; 1.0136x over previous
; #define LAS __attribute__((address_space(3)))
;     ...
;         if (k0 < qw + 32 && alive) {
;             const LAS unsigned char* kb = lds + AT_K + cur * 8192 + hi * 1024 + r32 * 16;
;             f32x16 p0, p1;
; #pragma unroll
;             for (int r = 0; r < 16; ++r) { p0[r] = 0.f; p1[r] = 0.f; }
; #pragma unroll
;             for (int d0 = 0; d0 < 4; ++d0) {
;                 const bf16x8 a0 = *(const LAS bf16x8*)(kb + d0 * 2048), a1 = *(const LAS bf16x8*)(kb + d0 * 2048 + 512);
;                 p0 = __builtin_amdgcn_mfma_f32_32x32x16_bf16(a0, qr[d0], p0, 0, 0, 0);
;                 p1 = __builtin_amdgcn_mfma_f32_32x32x16_bf16(a1, qr[d0], p1, 0, 0, 0);
;             }
; #pragma unroll
;             for (int r = 0; r < 16; ++r) { p0[r] = __builtin_amdgcn_rcpf(1.f + __builtin_amdgcn_exp2f(p0[r])); p1[r] = __builtin_amdgcn_rcpf(1.f + __builtin_amdgcn_exp2f(p1[r])); }
;             if (k0 + 63 >= qw) {
;                 const int kb0 = k0 + 16 * hi;
; #pragma unroll
;                 for (int r = 0; r < 16; ++r) { if (kb0 + r >= qrel) p0[r] = 1.f; if (kb0 + 32 + r >= qrel) p1[r] = 1.f; }
;             }
.LBB0_461:
	s_and_b32 s1, s6, 1
	s_cmp_le_i32 s27, s24
	s_cselect_b64 s[4:5], -1, 0
	v_cmp_ne_u32_e32 vcc, 0, v32
	s_and_b64 s[4:5], s[4:5], vcc
	s_andn2_b64 vcc, exec, s[4:5]
	s_cbranch_vccnz .LBB0_471
	v_lshl_add_u32 v94, s1, 13, v111
	s_mul_i32 s98, s1, 0x2400
	ds_read_b128 v[156:159], v94
	ds_read_b128 v[160:163], v94 offset:2048
	ds_read_b128 v[168:171], v94 offset:4096
	ds_read_b128 v[172:175], v94 offset:6144
	ds_read_b128 v[176:179], v94 offset:512
	ds_read_b128 v[180:183], v94 offset:2560
	ds_read_b128 v[184:187], v94 offset:4608
	ds_read_b128 v[188:191], v94 offset:6656
	v_add_u32_e32 v126, s98, v112
	s_add_i32 s4, s27, 63
	s_cmp_lt_i32 s4, s24
	s_waitcnt lgkmcnt(7)
	v_mfma_f32_32x32x16_bf16 v[32:47], v[156:159], v[66:69], 0
	ds_read_b128 v[206:209], v126 offset:16384
	s_waitcnt lgkmcnt(7)
	v_mfma_f32_32x32x16_bf16 v[32:47], v[160:163], v[70:73], v[32:47]
	ds_read_b128 v[210:213], v126 offset:20992
	s_waitcnt lgkmcnt(7)
	v_mfma_f32_32x32x16_bf16 v[32:47], v[168:171], v[74:77], v[32:47]
	ds_read_b128 v[214:217], v126 offset:16400
	s_waitcnt lgkmcnt(7)
	v_mfma_f32_32x32x16_bf16 v[32:47], v[172:175], v[78:81], v[32:47]
	ds_read_b128 v[218:221], v126 offset:21008
	s_waitcnt lgkmcnt(7)
	v_mfma_f32_32x32x16_bf16 v[48:63], v[176:179], v[66:69], 0
	ds_read_b128 v[222:225], v126 offset:16448
	s_waitcnt lgkmcnt(7)
	v_mfma_f32_32x32x16_bf16 v[48:63], v[180:183], v[70:73], v[48:63]
	ds_read_b128 v[226:229], v126 offset:21056
	s_waitcnt lgkmcnt(7)
	v_mfma_f32_32x32x16_bf16 v[48:63], v[184:187], v[74:77], v[48:63]
	ds_read_b128 v[118:121], v126 offset:16464
	s_waitcnt lgkmcnt(7)
	v_mfma_f32_32x32x16_bf16 v[48:63], v[188:191], v[78:81], v[48:63]
	ds_read_b128 v[122:125], v126 offset:21072
	v_exp_f32_e32 v32, v32
	v_exp_f32_e32 v33, v33
	v_exp_f32_e32 v34, v34
	v_exp_f32_e32 v35, v35
	v_exp_f32_e32 v36, v36
	v_exp_f32_e32 v37, v37
	v_exp_f32_e32 v38, v38
	v_exp_f32_e32 v39, v39
	v_exp_f32_e32 v40, v40
	v_exp_f32_e32 v41, v41
	v_exp_f32_e32 v42, v42
	v_exp_f32_e32 v43, v43
	v_exp_f32_e32 v44, v44
	v_exp_f32_e32 v45, v45
	v_exp_f32_e32 v46, v46
	v_exp_f32_e32 v47, v47
	v_exp_f32_e32 v48, v48
	v_exp_f32_e32 v49, v49
	v_exp_f32_e32 v50, v50
	v_exp_f32_e32 v51, v51
	v_exp_f32_e32 v52, v52
	v_exp_f32_e32 v53, v53
	v_exp_f32_e32 v54, v54
	v_exp_f32_e32 v55, v55
	v_exp_f32_e32 v56, v56
	v_exp_f32_e32 v57, v57
	v_exp_f32_e32 v58, v58
	v_exp_f32_e32 v59, v59
	v_exp_f32_e32 v60, v60
	v_exp_f32_e32 v61, v61
	v_exp_f32_e32 v62, v62
	v_exp_f32_e32 v63, v63
	s_cbranch_scc1 .Lattn_nomask
	v_sub_u32_e32 v230, v109, v64
	v_subrev_u32_e32 v230, s27, v230
	v_cmp_gt_i32_e64 s[42:43], v230, 0
	v_cmp_gt_i32_e64 s[44:45], v230, 1
	v_cmp_gt_i32_e64 s[46:47], v230, 2
	v_cmp_gt_i32_e64 s[48:49], v230, 3
	v_cndmask_b32_e64 v32, 0, v32, s[42:43]
	v_cndmask_b32_e64 v33, 0, v33, s[44:45]
	v_cndmask_b32_e64 v34, 0, v34, s[46:47]
	v_cndmask_b32_e64 v35, 0, v35, s[48:49]
	v_cmp_gt_i32_e64 s[42:43], v230, 4
	v_cmp_gt_i32_e64 s[44:45], v230, 5
	v_cmp_gt_i32_e64 s[46:47], v230, 6
	v_cmp_gt_i32_e64 s[48:49], v230, 7
	v_cndmask_b32_e64 v36, 0, v36, s[42:43]
	v_cndmask_b32_e64 v37, 0, v37, s[44:45]
	v_cndmask_b32_e64 v38, 0, v38, s[46:47]
	v_cndmask_b32_e64 v39, 0, v39, s[48:49]
	v_cmp_gt_i32_e64 s[42:43], v230, 8
	v_cmp_gt_i32_e64 s[44:45], v230, 9
	v_cmp_gt_i32_e64 s[46:47], v230, 10
	v_cmp_gt_i32_e64 s[48:49], v230, 11
	v_cndmask_b32_e64 v40, 0, v40, s[42:43]
	v_cndmask_b32_e64 v41, 0, v41, s[44:45]
	v_cndmask_b32_e64 v42, 0, v42, s[46:47]
	v_cndmask_b32_e64 v43, 0, v43, s[48:49]
	v_cmp_gt_i32_e64 s[42:43], v230, 12
	v_cmp_gt_i32_e64 s[44:45], v230, 13
	v_cmp_gt_i32_e64 s[46:47], v230, 14
	v_cmp_gt_i32_e64 s[48:49], v230, 15
	v_cndmask_b32_e64 v44, 0, v44, s[42:43]
	v_cndmask_b32_e64 v45, 0, v45, s[44:45]
	v_cndmask_b32_e64 v46, 0, v46, s[46:47]
	v_cndmask_b32_e64 v47, 0, v47, s[48:49]
	v_cmp_gt_i32_e64 s[42:43], v230, 32
	v_cmp_gt_i32_e64 s[44:45], v230, 33
	v_cmp_gt_i32_e64 s[46:47], v230, 34
	v_cmp_gt_i32_e64 s[48:49], v230, 35
	v_cndmask_b32_e64 v48, 0, v48, s[42:43]
	v_cndmask_b32_e64 v49, 0, v49, s[44:45]
	v_cndmask_b32_e64 v50, 0, v50, s[46:47]
	v_cndmask_b32_e64 v51, 0, v51, s[48:49]
	v_cmp_gt_i32_e64 s[42:43], v230, 36
	v_cmp_gt_i32_e64 s[44:45], v230, 37
	v_cmp_gt_i32_e64 s[46:47], v230, 38
	v_cmp_gt_i32_e64 s[48:49], v230, 39
	v_cndmask_b32_e64 v52, 0, v52, s[42:43]
	v_cndmask_b32_e64 v53, 0, v53, s[44:45]
	v_cndmask_b32_e64 v54, 0, v54, s[46:47]
	v_cndmask_b32_e64 v55, 0, v55, s[48:49]
	v_cmp_gt_i32_e64 s[42:43], v230, 40
	v_cmp_gt_i32_e64 s[44:45], v230, 41
	v_cmp_gt_i32_e64 s[46:47], v230, 42
	v_cmp_gt_i32_e64 s[48:49], v230, 43
	v_cndmask_b32_e64 v56, 0, v56, s[42:43]
	v_cndmask_b32_e64 v57, 0, v57, s[44:45]
	v_cndmask_b32_e64 v58, 0, v58, s[46:47]
	v_cndmask_b32_e64 v59, 0, v59, s[48:49]
	v_cmp_gt_i32_e64 s[42:43], v230, 44
	v_cmp_gt_i32_e64 s[44:45], v230, 45
	v_cmp_gt_i32_e64 s[46:47], v230, 46
	v_cmp_gt_i32_e64 s[48:49], v230, 47
	v_cndmask_b32_e64 v60, 0, v60, s[42:43]
	v_cndmask_b32_e64 v61, 0, v61, s[44:45]
	v_cndmask_b32_e64 v62, 0, v62, s[46:47]
	v_cndmask_b32_e64 v63, 0, v63, s[48:49]
; #define LAS __attribute__((address_space(3)))
; __device__ __forceinline__ unsigned pk2(float lo, float hi) { return pg8::cvt_pk_bf16(lo, hi); }
; #define AT_PV(W, off) do { const bf16x8 pf_ = __builtin_bit_cast(bf16x8, W); \
;                 const bf16x8 v0_ = *(const LAS bf16x8*)(vb + (off)), v1_ = *(const LAS bf16x8*)(vb + 4608 + (off)); \
;                 o0 = __builtin_amdgcn_mfma_f32_32x32x16_bf16(v0_, pf_, o0, 0, 0, 0); o1 = __builtin_amdgcn_mfma_f32_32x32x16_bf16(v1_, pf_, o1, 0, 0, 0); } while (0)
;     ...
; #pragma unroll
;             for (int r = 14; r >= 0; --r) { p0[r] *= p0[r + 1]; p1[r] *= p1[r + 1]; }
;             const float L0 = p0[0], L1 = p1[0];
;             const float pL0 = __shfl_xor(L0, 32), pL1 = __shfl_xor(L1, 32);
;             const float tot1 = L1 * pL1;
;             const float pre1 = hi ? C : C * pL1;
;             const float pre0 = C * tot1 * (hi ? 1.f : pL0);
;             C = C * tot1 * (L0 * pL0);
; #pragma unroll
;             for (int r = 0; r < 15; ++r) { p0[r] = pre0 * (p0[r + 1] - p0[r]); p1[r] = pre1 * (p1[r + 1] - p1[r]); }
;             p0[15] = pre0 * (1.f - p0[15]); p1[15] = pre1 * (1.f - p1[15]);
;             u32x4 w00, w01, w10, w11;
;             w00.x = pk2(p0[0], p0[1]); w00.y = pk2(p0[2], p0[3]); w00.z = pk2(p0[4], p0[5]); w00.w = pk2(p0[6], p0[7]);
;             w01.x = pk2(p0[8], p0[9]); w01.y = pk2(p0[10], p0[11]); w01.z = pk2(p0[12], p0[13]); w01.w = pk2(p0[14], p0[15]);
;             w10.x = pk2(p1[0], p1[1]); w10.y = pk2(p1[2], p1[3]); w10.z = pk2(p1[4], p1[5]); w10.w = pk2(p1[6], p1[7]);
;             w11.x = pk2(p1[8], p1[9]); w11.y = pk2(p1[10], p1[11]); w11.z = pk2(p1[12], p1[13]); w11.w = pk2(p1[14], p1[15]);
;             const LAS unsigned char* vb = lds + AT_V + cur * 9216 + r32 * 144 + hi * 32;
;     ...
;             AT_PV(w00, 0); AT_PV(w01, 16); AT_PV(w10, 64); AT_PV(w11, 80);
;     ...
;             alive = __any(C != 0.f);
.Lattn_nomask:
	v_add_f32_e32 v156, 1.0, v32
	v_add_f32_e32 v176, 1.0, v48
	v_add_f32_e32 v157, 1.0, v33
	v_add_f32_e32 v177, 1.0, v49
	v_add_f32_e32 v158, 1.0, v34
	v_add_f32_e32 v178, 1.0, v50
	v_add_f32_e32 v159, 1.0, v35
	v_add_f32_e32 v179, 1.0, v51
	v_add_f32_e32 v160, 1.0, v36
	v_add_f32_e32 v180, 1.0, v52
	v_add_f32_e32 v161, 1.0, v37
	v_add_f32_e32 v181, 1.0, v53
	v_add_f32_e32 v162, 1.0, v38
	v_add_f32_e32 v182, 1.0, v54
	v_add_f32_e32 v163, 1.0, v39
	v_add_f32_e32 v183, 1.0, v55
	v_add_f32_e32 v168, 1.0, v40
	v_add_f32_e32 v184, 1.0, v56
	v_add_f32_e32 v169, 1.0, v41
	v_add_f32_e32 v185, 1.0, v57
	v_add_f32_e32 v170, 1.0, v42
	v_add_f32_e32 v186, 1.0, v58
	v_add_f32_e32 v171, 1.0, v43
	v_add_f32_e32 v187, 1.0, v59
	v_add_f32_e32 v172, 1.0, v44
	v_add_f32_e32 v188, 1.0, v60
	v_add_f32_e32 v173, 1.0, v45
	v_add_f32_e32 v189, 1.0, v61
	v_add_f32_e32 v174, 1.0, v46
	v_add_f32_e32 v190, 1.0, v62
	v_add_f32_e32 v175, 1.0, v47
	v_add_f32_e32 v191, 1.0, v63
	v_xor_b32_e32 v94, 32, v236
	v_lshlrev_b32_e32 v94, 2, v94
	v_mul_f32_e32 v157, v156, v157
	v_mul_f32_e32 v169, v168, v169
	v_mul_f32_e32 v177, v176, v177
	v_mul_f32_e32 v185, v184, v185
	v_mul_f32_e32 v158, v157, v158
	v_mul_f32_e32 v170, v169, v170
	v_mul_f32_e32 v178, v177, v178
	v_mul_f32_e32 v186, v185, v186
	v_mul_f32_e32 v159, v158, v159
	v_mul_f32_e32 v171, v170, v171
	v_mul_f32_e32 v179, v178, v179
	v_mul_f32_e32 v187, v186, v187
	v_mul_f32_e32 v160, v159, v160
	v_mul_f32_e32 v172, v171, v172
	v_mul_f32_e32 v180, v179, v180
	v_mul_f32_e32 v188, v187, v188
	v_mul_f32_e32 v161, v160, v161
	v_mul_f32_e32 v173, v172, v173
	v_mul_f32_e32 v181, v180, v181
	v_mul_f32_e32 v189, v188, v189
	v_mul_f32_e32 v162, v161, v162
	v_mul_f32_e32 v174, v173, v174
	v_mul_f32_e32 v182, v181, v182
	v_mul_f32_e32 v190, v189, v190
	v_mul_f32_e32 v163, v162, v163
	v_mul_f32_e32 v175, v174, v175
	v_mul_f32_e32 v183, v182, v183
	v_mul_f32_e32 v191, v190, v191
	v_rcp_f32_e32 v246, v163
	v_rcp_f32_e32 v247, v175
	v_rcp_f32_e32 v248, v183
	v_rcp_f32_e32 v249, v191
	v_mul_f32_e32 v33, v156, v33
	v_mul_f32_e32 v41, v168, v41
	v_mul_f32_e32 v49, v176, v49
	v_mul_f32_e32 v57, v184, v57
	v_mul_f32_e32 v250, v246, v247
	v_mul_f32_e32 v251, v248, v249
	v_mul_f32_e32 v34, v157, v34
	v_mul_f32_e32 v42, v169, v42
	v_mul_f32_e32 v50, v177, v50
	v_mul_f32_e32 v58, v185, v58
	ds_bpermute_b32 v230, v94, v250
	ds_bpermute_b32 v231, v94, v251
	v_mul_f32_e32 v35, v158, v35
	v_mul_f32_e32 v43, v170, v43
	v_mul_f32_e32 v51, v178, v51
	v_mul_f32_e32 v59, v186, v59
	v_mul_f32_e32 v36, v159, v36
	v_mul_f32_e32 v44, v171, v44
	v_mul_f32_e32 v52, v179, v52
	v_mul_f32_e32 v60, v187, v60
	v_mul_f32_e32 v37, v160, v37
	v_mul_f32_e32 v45, v172, v45
	v_mul_f32_e32 v53, v180, v53
	v_mul_f32_e32 v61, v188, v61
	v_mul_f32_e32 v38, v161, v38
	v_mul_f32_e32 v46, v173, v46
	v_mul_f32_e32 v54, v181, v54
	v_mul_f32_e32 v62, v189, v62
	v_mul_f32_e32 v39, v162, v39
	v_mul_f32_e32 v47, v174, v47
	v_mul_f32_e32 v55, v182, v55
	v_mul_f32_e32 v63, v190, v63
	s_waitcnt lgkmcnt(0)
	v_mul_f32_e32 v237, v251, v231
	v_mul_f32_e32 v238, v95, v231
	v_cndmask_b32_e64 v239, 1.0, v230, s[36:37]
	v_mul_f32_e32 v237, v95, v237
	v_cndmask_b32_e64 v238, v95, v238, s[36:37]
	v_mul_f32_e32 v230, v250, v230
	v_mul_f32_e32 v239, v237, v239
	v_mul_f32_e32 v95, v237, v230
	v_mul_f32_e32 v239, v239, v247
	v_mul_f32_e32 v238, v238, v249
	v_cmp_neq_f32_e32 vcc, 0, v95
	v_mul_f32_e32 v237, v239, v246
	v_mul_f32_e32 v231, v238, v248
	s_cmp_lg_u64 vcc, 0
	s_cselect_b64 s[4:5], -1, 0
	v_mul_f32_e32 v32, v237, v32
	v_mul_f32_e32 v33, v237, v33
	v_mul_f32_e32 v34, v237, v34
	v_mul_f32_e32 v35, v237, v35
	v_mul_f32_e32 v36, v237, v36
	v_mul_f32_e32 v37, v237, v37
	v_mul_f32_e32 v38, v237, v38
	v_mul_f32_e32 v39, v237, v39
	v_mul_f32_e32 v40, v239, v40
	v_mul_f32_e32 v41, v239, v41
	v_mul_f32_e32 v42, v239, v42
	v_mul_f32_e32 v43, v239, v43
	v_mul_f32_e32 v44, v239, v44
	v_mul_f32_e32 v45, v239, v45
	v_mul_f32_e32 v46, v239, v46
	v_mul_f32_e32 v47, v239, v47
	v_mul_f32_e32 v48, v231, v48
	v_mul_f32_e32 v49, v231, v49
	v_mul_f32_e32 v50, v231, v50
	v_mul_f32_e32 v51, v231, v51
	v_mul_f32_e32 v52, v231, v52
	v_mul_f32_e32 v53, v231, v53
	v_mul_f32_e32 v54, v231, v54
	v_mul_f32_e32 v55, v231, v55
	v_mul_f32_e32 v56, v238, v56
	v_mul_f32_e32 v57, v238, v57
	v_mul_f32_e32 v58, v238, v58
	v_mul_f32_e32 v59, v238, v59
	v_mul_f32_e32 v60, v238, v60
	v_mul_f32_e32 v61, v238, v61
	v_mul_f32_e32 v62, v238, v62
	v_mul_f32_e32 v63, v238, v63
	v_cvt_pk_bf16_f32 v142, v32, v33
	v_cvt_pk_bf16_f32 v143, v34, v35
	v_cvt_pk_bf16_f32 v144, v36, v37
	v_cvt_pk_bf16_f32 v145, v38, v39
	v_cvt_pk_bf16_f32 v146, v40, v41
	v_cvt_pk_bf16_f32 v147, v42, v43
	v_cvt_pk_bf16_f32 v148, v44, v45
	v_cvt_pk_bf16_f32 v149, v46, v47
	v_cvt_pk_bf16_f32 v150, v48, v49
	v_cvt_pk_bf16_f32 v151, v50, v51
	v_cvt_pk_bf16_f32 v152, v52, v53
	v_cvt_pk_bf16_f32 v153, v54, v55
	v_cvt_pk_bf16_f32 v242, v56, v57
	v_cvt_pk_bf16_f32 v243, v58, v59
	v_cvt_pk_bf16_f32 v244, v60, v61
	v_cvt_pk_bf16_f32 v245, v62, v63
	v_mfma_f32_32x32x16_bf16 v[16:31], v[206:209], v[142:145], v[16:31]
	v_mfma_f32_32x32x16_bf16 v[0:15], v[210:213], v[142:145], v[0:15]
	v_mfma_f32_32x32x16_bf16 v[16:31], v[214:217], v[146:149], v[16:31]
	v_mfma_f32_32x32x16_bf16 v[0:15], v[218:221], v[146:149], v[0:15]
	v_mfma_f32_32x32x16_bf16 v[16:31], v[222:225], v[150:153], v[16:31]
	v_mfma_f32_32x32x16_bf16 v[0:15], v[226:229], v[150:153], v[0:15]
	v_mfma_f32_32x32x16_bf16 v[16:31], v[118:121], v[242:245], v[16:31]
	v_mfma_f32_32x32x16_bf16 v[0:15], v[122:125], v[242:245], v[0:15]
	v_cndmask_b32_e64 v32, 0, 1, s[4:5]
	s_andn2_b64 vcc, exec, s[12:13]
	s_cbranch_vccz .LBB0_472
